# speedup vs baseline: 1.0007x; 1.0007x over previous
; DI float h2lo(unsigned u) { return (float)__builtin_bit_cast(f16x2_t, u)[0]; }
; DI float h2hi(unsigned u) { return (float)__builtin_bit_cast(f16x2_t, u)[1]; }
; DI int my_tid() { int t = tid_raw(); asm volatile("" : "+v"(t)); return t; }
; DI float shfl_xor_l(float v, int mask, int lane) { return __int_as_float(__builtin_amdgcn_ds_bpermute((lane ^ mask) << 2, __float_as_int(v))); }
; DI void ln_phase(const Params& p, const u16* src, const float* g, const float* b, float* dstf, u16* dstb) {
;   const int lane = my_tid() & 63, wid = my_tid() >> 6;
;   const int stride = gridDim.x * 8;
;   int row = blockIdx.x * 8 + wid;
;   u32x2 raw[4], nxt[4];
;   f32x4 gv[4], bv[4];
; #pragma unroll
;   for (int i = 0; i < 4; ++i) { gv[i] = *(const f32x4*)(g + i * 256 + lane * 4); bv[i] = *(const f32x4*)(b + i * 256 + lane * 4); }
;   if (row < S) {
; #pragma unroll
;     for (int i = 0; i < 4; ++i) raw[i] = *(const u32x2*)(src + (size_t)row * D + i * 256 + lane * 4);
;   }
;   for (; row < S; row += stride) {
;     const int rn = row + stride;
;     if (rn < S) {
; #pragma unroll
;       for (int i = 0; i < 4; ++i) nxt[i] = *(const u32x2*)(src + (size_t)rn * D + i * 256 + lane * 4);
;     }
;     f32x4 v[4];
;     float s = 0.f;
; #pragma unroll
;     for (int i = 0; i < 4; ++i) { v[i] = (f32x4){h2lo(raw[i][0]), h2hi(raw[i][0]), h2lo(raw[i][1]), h2hi(raw[i][1])}; s += (v[i][0] + v[i][1]) + (v[i][2] + v[i][3]); }
; #pragma unroll
;     for (int o = 32; o >= 1; o >>= 1) s += shfl_xor_l(s, o, lane);
.LBB0_1109:
	s_movk_i32 s59, 0x3c0
	s_movk_i32 s58, 0x3000
	s_or_b64 exec, exec, s[8:9]
	s_waitcnt lgkmcnt(0)
	s_barrier
	s_getreg_b32 s2, hwreg(HW_REG_HW_ID, 0, 6)
	s_lshl_b32 s2, s2, 2
	s_and_b32 s2, s2, 0xfc
	s_add_i32 s2, s2, 0x20040
	v_mov_b32_e32 v0, s2
	ds_read_b32 v0, v0
	s_lshl_b32 s92, s69, 10
	s_waitcnt lgkmcnt(0)
	v_readfirstlane_b32 s2, v0
	s_nop 1
	v_lshl_or_b32 v34, s2, 6, v214
	s_getreg_b32 s2, hwreg(HW_REG_HW_ID, 0, 6)
	s_lshl_b32 s2, s2, 2
	s_and_b32 s2, s2, 0xfc
	s_add_i32 s2, s2, 0x20040
	v_mov_b32_e32 v0, s2
	ds_read_b32 v0, v0
	s_waitcnt lgkmcnt(0)
	v_readfirstlane_b32 s2, v0
	s_nop 1
	v_lshl_or_b32 v0, s2, 6, v214
	v_readlane_b32 s2, v255, 12
	v_ashrrev_i32_e32 v36, 6, v0
	s_nop 0
	v_add_u32_e32 v32, s2, v36
	s_movk_i32 s2, 0x4000
	v_cmp_gt_i32_e32 vcc, s2, v32
	s_and_saveexec_b64 s[8:9], vcc
	s_cbranch_execz .LBB0_1114
	s_lshl_b64 s[2:3], s[92:93], 2
	v_readlane_b32 s36, v252, 18
	v_readlane_b32 s37, v252, 19
	s_add_u32 s22, s36, s2
	v_readlane_b32 s38, v252, 20
	s_addc_u32 s23, s37, s3
	v_lshlrev_b32_e32 v35, 2, v34
	v_readlane_b32 s39, v252, 21
	s_add_u32 s2, s38, s2
	v_and_b32_e32 v37, 0xfc, v35
	s_addc_u32 s3, s39, s3
	v_lshlrev_b32_e32 v28, 2, v37
	global_load_dwordx4 v[0:3], v28, s[22:23]
	global_load_dwordx4 v[4:7], v28, s[22:23] offset:1024
	global_load_dwordx4 v[8:11], v28, s[2:3]
	global_load_dwordx4 v[12:15], v28, s[2:3] offset:1024
	global_load_dwordx4 v[16:19], v28, s[22:23] offset:2048
	global_load_dwordx4 v[20:23], v28, s[22:23] offset:3072
	global_load_dwordx4 v[24:27], v28, s[2:3] offset:2048
	s_nop 0
	global_load_dwordx4 v[28:31], v28, s[2:3] offset:3072
	v_ashrrev_i32_e32 v33, 31, v32
	v_readlane_b32 s2, v254, 14
	v_lshlrev_b64 v[38:39], 11, v[32:33]
	v_readlane_b32 s3, v254, 15
	v_lshlrev_b32_e32 v64, 1, v37
	v_bfrev_b32_e32 v37, 0.5
	v_lshl_add_u64 v[40:41], s[2:3], 0, v[38:39]
	v_lshl_add_u64 v[40:41], v[40:41], 0, v[64:65]
	v_lshl_add_u64 v[82:83], v[40:41], 0, v[64:65]
	v_readfirstlane_b32 s100, v36
	v_readlane_b32 s101, v255, 14
	s_lshl_b32 s100, s100, 14
	s_nop 0
	v_mov_b32_e32 v86, s101
	v_readlane_b32 s101, v255, 15
	v_add_u32_e32 v84, s100, v64
	s_nop 1
	v_mov_b32_e32 v87, s101
	s_mov_b32 m0, s100
	s_nop 0
	global_load_lds_dwordx4 v[82:83], off
	global_load_lds_dwordx4 v[82:83], off offset:1024
	v_lshl_add_u64 v[82:83], v[82:83], 0, v[86:87]
	s_add_u32 s100, s100, 0x800
	s_mov_b32 m0, s100
	s_nop 0
	global_load_lds_dwordx4 v[82:83], off
	global_load_lds_dwordx4 v[82:83], off offset:1024
	v_lshl_add_u64 v[82:83], v[82:83], 0, v[86:87]
	s_add_u32 s100, s100, 0x800
	s_mov_b32 m0, s100
	s_nop 0
	global_load_lds_dwordx4 v[82:83], off
	global_load_lds_dwordx4 v[82:83], off offset:1024
	v_lshl_add_u64 v[82:83], v[82:83], 0, v[86:87]
	s_add_u32 s100, s100, 0x800
	s_mov_b32 m0, s100
	s_nop 0
	global_load_lds_dwordx4 v[82:83], off
	global_load_lds_dwordx4 v[82:83], off offset:1024
	v_lshl_add_u64 v[82:83], v[82:83], 0, v[86:87]
	s_add_u32 s100, s100, 0x800
	s_mov_b32 m0, s100
	s_nop 0
	global_load_lds_dwordx4 v[82:83], off
	global_load_lds_dwordx4 v[82:83], off offset:1024
	v_lshl_add_u64 v[82:83], v[82:83], 0, v[86:87]
	s_add_u32 s100, s100, 0x800
	s_mov_b32 m0, s100
	s_nop 0
	global_load_lds_dwordx4 v[82:83], off
	global_load_lds_dwordx4 v[82:83], off offset:1024
	v_lshl_add_u64 v[82:83], v[82:83], 0, v[86:87]
	s_add_u32 s100, s100, 0x800
	s_mov_b32 m0, s100
	s_nop 0
	global_load_lds_dwordx4 v[82:83], off
	global_load_lds_dwordx4 v[82:83], off offset:1024
	v_lshl_add_u64 v[82:83], v[82:83], 0, v[86:87]
	s_add_u32 s100, s100, 0x800
	s_mov_b32 m0, s100
	s_nop 0
	global_load_lds_dwordx4 v[82:83], off
	global_load_lds_dwordx4 v[82:83], off offset:1024
	s_movk_i32 s2, 0x80
	v_bitop3_b32 v33, v35, s2, v37 bitop3:0x6c
	v_readlane_b32 s2, v255, 13
	v_bitop3_b32 v54, v35, 64, v37 bitop3:0x6c
	v_bitop3_b32 v55, v35, 32, v37 bitop3:0x6c
	v_add_u32_e32 v36, s2, v36
	v_bitop3_b32 v56, v35, 16, v37 bitop3:0x6c
	v_bitop3_b32 v57, v35, 8, v37 bitop3:0x6c
	v_bitop3_b32 v58, v35, 4, v37 bitop3:0x6c
	v_and_b32_e32 v34, 63, v34
	v_ashrrev_i32_e32 v37, 31, v36
	v_lshlrev_b32_e32 v64, 3, v34
	v_lshl_add_u64 v[34:35], s[90:91], 0, v[38:39]
	v_lshlrev_b64 v[36:37], 11, v[36:37]
	v_mov_b32_e32 v38, 0
	v_lshl_add_u64 v[36:37], s[90:91], 0, v[36:37]
	s_mov_b64 s[22:23], 0
	v_mov_b32_e32 v39, v38
	v_mov_b32_e32 v40, v38
	v_mov_b32_e32 v41, v38
	v_mov_b32_e32 v42, v38
	v_mov_b32_e32 v43, v38
	v_mov_b32_e32 v44, v38
	v_mov_b32_e32 v45, v38
	v_readlane_b32 s40, v252, 22
	v_readlane_b32 s41, v252, 23
	v_readlane_b32 s42, v252, 24
	v_readlane_b32 s43, v252, 25
	v_readlane_b32 s44, v252, 26
	v_readlane_b32 s45, v252, 27
	v_readlane_b32 s46, v252, 28
	v_readlane_b32 s47, v252, 29
	v_readlane_b32 s48, v252, 30
	v_readlane_b32 s49, v252, 31
	v_readlane_b32 s50, v252, 32
	v_readlane_b32 s51, v252, 33
	s_branch .LBB0_1112
; DI float h2lo(unsigned u) { return (float)__builtin_bit_cast(f16x2_t, u)[0]; }
; DI float h2hi(unsigned u) { return (float)__builtin_bit_cast(f16x2_t, u)[1]; }
; DI float shfl_xor_l(float v, int mask, int lane) { return __int_as_float(__builtin_amdgcn_ds_bpermute((lane ^ mask) << 2, __float_as_int(v))); }
; DI void ln_phase(const Params& p, const u16* src, const float* g, const float* b, float* dstf, u16* dstb) {
;     ...
;     f32x4 v[4];
;     float s = 0.f;
; #pragma unroll
;     for (int i = 0; i < 4; ++i) { v[i] = (f32x4){h2lo(raw[i][0]), h2hi(raw[i][0]), h2lo(raw[i][1]), h2hi(raw[i][1])}; s += (v[i][0] + v[i][1]) + (v[i][2] + v[i][3]); }
; #pragma unroll
;     for (int o = 32; o >= 1; o >>= 1) s += shfl_xor_l(s, o, lane);
;     const float mu = s * (1.0f / 1024.0f);
;     float q = 0.f;
; #pragma unroll
;     for (int i = 0; i < 4; ++i) { v[i] = v[i] - mu; q += (v[i][0] * v[i][0] + v[i][1] * v[i][1]) + (v[i][2] * v[i][2] + v[i][3] * v[i][3]); }
.LBB0_1111:
	s_or_b64 exec, exec, s[28:29]
	s_waitcnt vmcnt(14)
	ds_read_b64 v[52:53], v84
	ds_read_b64 v[50:51], v84 offset:512
	ds_read_b64 v[48:49], v84 offset:1024
	ds_read_b64 v[46:47], v84 offset:1536
	v_add_u32_e32 v84, 0x800, v84
	s_waitcnt lgkmcnt(0)
	v_cvt_f32_f16_sdwa v60, v52 dst_sel:DWORD dst_unused:UNUSED_PAD src0_sel:WORD_1
	v_cvt_f32_f16_e32 v62, v52
	v_cvt_f32_f16_sdwa v61, v53 dst_sel:DWORD dst_unused:UNUSED_PAD src0_sel:WORD_1
	v_cvt_f32_f16_e32 v63, v53
	v_cvt_f32_f16_e32 v66, v50
	v_cvt_f32_f16_e32 v67, v51
	v_cvt_f32_f16_sdwa v68, v46 dst_sel:DWORD dst_unused:UNUSED_PAD src0_sel:WORD_1
	v_pk_add_f32 v[60:61], v[62:63], v[60:61]
	v_cvt_f32_f16_sdwa v62, v50 dst_sel:DWORD dst_unused:UNUSED_PAD src0_sel:WORD_1
	v_cvt_f32_f16_sdwa v63, v51 dst_sel:DWORD dst_unused:UNUSED_PAD src0_sel:WORD_1
	v_add_f32_e32 v59, v60, v61
	v_add_f32_e32 v61, 0, v59
	v_cvt_f32_f16_sdwa v59, v48 dst_sel:DWORD dst_unused:UNUSED_PAD src0_sel:WORD_1
	v_pk_add_f32 v[62:63], v[66:67], v[62:63]
	v_cvt_f32_f16_e32 v60, v48
	v_pk_add_f32 v[62:63], v[62:63], v[62:63] op_sel_hi:[0,1]
	v_cvt_f32_f16_sdwa v62, v49 dst_sel:DWORD dst_unused:UNUSED_PAD src0_sel:WORD_1
	v_cvt_f32_f16_e32 v66, v49
	v_add_f32_e32 v67, v60, v59
	v_cvt_f32_f16_sdwa v60, v47 dst_sel:DWORD dst_unused:UNUSED_PAD src0_sel:WORD_1
	s_and_b64 s[2:3], exec, s[38:39]
	v_add_f32_e32 v69, v66, v62
	v_cvt_f32_f16_e32 v66, v46
	v_cvt_f32_f16_e32 v62, v47
	s_or_b64 s[22:23], s[2:3], s[22:23]
	v_pk_add_f32 v[66:67], v[66:67], v[68:69]
	v_pk_add_f32 v[60:61], v[62:63], v[60:61]
	s_nop 0
	v_pk_add_f32 v[60:61], v[66:67], v[60:61]
	s_nop 0
	v_add_f32_e32 v59, v60, v61
	s_nop 1
	v_add_f32_dpp v59, v59, v59 quad_perm:[1,0,3,2] row_mask:0xf bank_mask:0xf
	s_nop 1
	v_add_f32_dpp v59, v59, v59 quad_perm:[2,3,0,1] row_mask:0xf bank_mask:0xf
	s_nop 1
	v_add_f32_dpp v59, v59, v59 row_half_mirror row_mask:0xf bank_mask:0xf
	s_nop 1
	v_add_f32_dpp v59, v59, v59 row_mirror row_mask:0xf bank_mask:0xf
	v_mov_b32_e32 v60, v59
	s_nop 1
	v_permlane16_swap_b32 v60, v59
	v_add_f32_e32 v59, v59, v60
	v_mov_b32_e32 v60, v59
	s_nop 1
	v_permlane32_swap_b32 v60, v59
	v_add_f32_e32 v59, v59, v60
	v_fma_mix_f32 v61, v59, s65, v52 op_sel:[0,0,1] op_sel_hi:[0,0,1]
	v_fma_mix_f32 v60, v59, s65, v52 op_sel_hi:[0,0,1]
	v_fma_mix_f32 v63, v59, s65, v53 op_sel:[0,0,1] op_sel_hi:[0,0,1]
	v_fma_mix_f32 v62, v59, s65, v53 op_sel_hi:[0,0,1]
	v_pk_mul_f32 v[52:53], v[62:63], v[62:63]
	v_pk_mul_f32 v[66:67], v[60:61], v[60:61]
	v_fma_mix_f32 v77, v59, s65, v47 op_sel:[0,0,1] op_sel_hi:[0,0,1]
	v_pk_mov_b32 v[68:69], v[66:67], v[52:53] op_sel:[1,0]
	v_mov_b32_e32 v67, v53
	v_pk_add_f32 v[52:53], v[68:69], v[66:67]
	v_fma_mix_f32 v67, v59, s65, v50 op_sel:[0,0,1] op_sel_hi:[0,0,1]
	v_fma_mix_f32 v66, v59, s65, v50 op_sel_hi:[0,0,1]
	v_fma_mix_f32 v69, v59, s65, v51 op_sel:[0,0,1] op_sel_hi:[0,0,1]
	v_fma_mix_f32 v68, v59, s65, v51 op_sel_hi:[0,0,1]
	v_pk_mul_f32 v[50:51], v[68:69], v[68:69]
	v_pk_mul_f32 v[70:71], v[66:67], v[66:67]
	v_pk_add_f32 v[52:53], v[52:53], v[52:53] op_sel_hi:[0,1]
	v_pk_mov_b32 v[72:73], v[70:71], v[50:51] op_sel:[1,0]
	v_mov_b32_e32 v71, v51
	v_pk_add_f32 v[50:51], v[72:73], v[70:71]
	v_fma_mix_f32 v70, v59, s65, v48 op_sel_hi:[0,0,1]
	v_fma_mix_f32 v71, v59, s65, v48 op_sel:[0,0,1] op_sel_hi:[0,0,1]
	v_mul_f32_e32 v48, v70, v70
	v_fma_mix_f32 v73, v59, s65, v49 op_sel:[0,0,1] op_sel_hi:[0,0,1]
	v_fma_mix_f32 v72, v59, s65, v49 op_sel_hi:[0,0,1]
	v_pk_fma_f32 v[48:49], v[70:71], v[70:71], v[48:49] op_sel_hi:[1,1,0]
	v_pk_add_f32 v[50:51], v[50:51], v[50:51] op_sel_hi:[0,1]
	v_mul_f32_e32 v48, v72, v72
	v_pk_fma_f32 v[74:75], v[72:73], v[72:73], v[48:49] op_sel_hi:[1,1,0]
	v_fma_mix_f32 v76, v59, s65, v47 op_sel_hi:[0,0,1]
; DI unsigned pk_bf16(float lo, float hi) { f32x2_t v = {lo, hi}; return __builtin_bit_cast(unsigned, __builtin_convertvector(v, bf16x2_t)); }
; DI float shfl_xor_l(float v, int mask, int lane) { return __int_as_float(__builtin_amdgcn_ds_bpermute((lane ^ mask) << 2, __float_as_int(v))); }
; DI void ln_phase(const Params& p, const u16* src, const float* g, const float* b, float* dstf, u16* dstb) {
;     ...
; #pragma unroll
;     for (int o = 32; o >= 1; o >>= 1) q += shfl_xor_l(q, o, lane);
;     const float rstd = 1.0f / sqrtf(q * (1.0f / 1024.0f) + 1e-5f);
; #pragma unroll
;     for (int i = 0; i < 4; ++i) {
;       const int col = i * 256 + lane * 4;
;       const f32x4 o = v[i] * rstd * gv[i] + bv[i];
;       if (dstf) *(f32x4*)(dstf + (size_t)row * D + col) = o;
;       if (dstb) { u32x2 ob; ob[0] = pk_bf16(o[0], o[1]); ob[1] = pk_bf16(o[2], o[3]); *(u32x2*)(dstb + (size_t)row * D + col) = ob; }
;     }
; #pragma unroll
;     for (int i = 0; i < 4; ++i) raw[i] = nxt[i];
;   }
	v_fma_mix_f32 v47, v59, s65, v46 op_sel:[0,0,1] op_sel_hi:[0,0,1]
	v_fma_mix_f32 v46, v59, s65, v46 op_sel_hi:[0,0,1]
	v_mul_f32_e32 v48, v46, v46
	v_mul_f32_e32 v74, v47, v47
	v_mul_f32_e32 v52, v76, v76
	v_mul_f32_e32 v50, v77, v77
	v_pk_add_f32 v[48:49], v[48:49], v[74:75]
	v_pk_add_f32 v[50:51], v[52:53], v[50:51]
	s_nop 0
	v_pk_add_f32 v[48:49], v[48:49], v[50:51]
	s_nop 0
	v_add_f32_e32 v48, v48, v49
	s_nop 1
	v_add_f32_dpp v48, v48, v48 quad_perm:[1,0,3,2] row_mask:0xf bank_mask:0xf
	s_nop 1
	v_add_f32_dpp v48, v48, v48 quad_perm:[2,3,0,1] row_mask:0xf bank_mask:0xf
	s_nop 1
	v_add_f32_dpp v48, v48, v48 row_half_mirror row_mask:0xf bank_mask:0xf
	s_nop 1
	v_add_f32_dpp v48, v48, v48 row_mirror row_mask:0xf bank_mask:0xf
	v_mov_b32_e32 v49, v48
	s_nop 1
	v_permlane16_swap_b32 v49, v48
	v_add_f32_e32 v48, v48, v49
	v_mov_b32_e32 v49, v48
	s_nop 1
	v_permlane32_swap_b32 v49, v48
	v_add_f32_e32 v48, v48, v49
	v_mov_b32_e32 v49, 0x3727c5ac
	v_fmamk_f32 v48, v48, 0x3a800000, v49
	v_cmp_gt_f32_e32 vcc, s66, v48
	v_mul_f32_e32 v49, 0x4f800000, v48
	s_nop 0
	v_cndmask_b32_e32 v48, v48, v49, vcc
	v_sqrt_f32_e32 v49, v48
	s_nop 0
	v_add_u32_e32 v50, -1, v49
	v_fma_f32 v51, -v50, v49, v48
	v_cmp_ge_f32_e64 s[38:39], 0, v51
	v_add_u32_e32 v51, 1, v49
	s_nop 0
	v_cndmask_b32_e64 v50, v49, v50, s[38:39]
	v_fma_f32 v49, -v51, v49, v48
	v_cmp_lt_f32_e64 s[38:39], 0, v49
	s_nop 1
	v_cndmask_b32_e64 v49, v50, v51, s[38:39]
	v_mul_f32_e32 v50, 0x37800000, v49
	v_cndmask_b32_e32 v49, v49, v50, vcc
	v_mov_b32_e32 v50, 0x260
	v_cmp_class_f32_e32 vcc, v48, v50
	s_nop 1
	v_cndmask_b32_e32 v48, v49, v48, vcc
	v_div_scale_f32 v49, s[2:3], v48, v48, 1.0
	v_rcp_f32_e32 v50, v49
	s_mov_b32 s2, 0xaa80000
	v_fma_f32 v51, -v49, v50, 1.0
	v_fmac_f32_e32 v50, v51, v50
	v_div_scale_f32 v51, vcc, 1.0, v48, 1.0
	v_mul_f32_e32 v52, v51, v50
	v_fma_f32 v53, -v49, v52, v51
	v_fmac_f32_e32 v52, v53, v50
	v_fma_f32 v49, -v49, v52, v51
	v_div_fmas_f32 v49, v49, v50, v52
	v_div_fixup_f32 v48, v49, v48, 1.0
	v_pk_mul_f32 v[50:51], v[60:61], v[48:49] op_sel_hi:[1,0]
	v_pk_mul_f32 v[52:53], v[62:63], v[48:49] op_sel_hi:[1,0]
	v_pk_fma_f32 v[50:51], v[0:1], v[50:51], v[8:9]
	v_pk_fma_f32 v[52:53], v[2:3], v[52:53], v[10:11]
	v_cvt_pk_bf16_f32 v50, v50, v51
	v_cvt_pk_bf16_f32 v51, v52, v53
	v_lshl_add_u64 v[52:53], v[34:35], 0, v[64:65]
	v_add_co_u32_e32 v52, vcc, s2, v52
	v_pk_mul_f32 v[60:61], v[68:69], v[48:49] op_sel_hi:[1,0]
	s_nop 0
	v_addc_co_u32_e32 v53, vcc, 0, v53, vcc
	global_store_dwordx2 v[52:53], v[50:51], off
	v_pk_mul_f32 v[50:51], v[66:67], v[48:49] op_sel_hi:[1,0]
	v_pk_fma_f32 v[60:61], v[6:7], v[60:61], v[14:15]
	v_pk_fma_f32 v[50:51], v[4:5], v[50:51], v[12:13]
	v_pk_mul_f32 v[46:47], v[46:47], v[48:49] op_sel_hi:[1,0]
	v_cvt_pk_bf16_f32 v50, v50, v51
	v_cvt_pk_bf16_f32 v51, v60, v61
	global_store_dwordx2 v[52:53], v[50:51], off offset:512
	v_pk_mul_f32 v[50:51], v[70:71], v[48:49] op_sel_hi:[1,0]
	v_pk_mul_f32 v[60:61], v[72:73], v[48:49] op_sel_hi:[1,0]
	v_pk_mul_f32 v[48:49], v[76:77], v[48:49] op_sel_hi:[1,0]
	v_pk_fma_f32 v[60:61], v[18:19], v[60:61], v[26:27]
	v_pk_fma_f32 v[50:51], v[16:17], v[50:51], v[24:25]
	v_pk_fma_f32 v[48:49], v[22:23], v[48:49], v[30:31]
	v_pk_fma_f32 v[46:47], v[20:21], v[46:47], v[28:29]
	v_readlane_b32 s2, v255, 14
	v_cvt_pk_bf16_f32 v50, v50, v51
	v_cvt_pk_bf16_f32 v51, v60, v61
	v_cvt_pk_bf16_f32 v46, v46, v47
	v_cvt_pk_bf16_f32 v47, v48, v49
	v_readlane_b32 s3, v255, 15
	global_store_dwordx2 v[52:53], v[50:51], off offset:1024
	global_store_dwordx2 v[52:53], v[46:47], off offset:1536
	v_lshl_add_u64 v[34:35], v[34:35], 0, s[2:3]
	v_lshl_add_u64 v[36:37], v[36:37], 0, s[2:3]
	s_andn2_b64 exec, exec, s[22:23]
	s_cbranch_execz .LBB0_1114

; DI float h2lo(unsigned u) { return (float)__builtin_bit_cast(f16x2_t, u)[0]; }
; DI float h2hi(unsigned u) { return (float)__builtin_bit_cast(f16x2_t, u)[1]; }
; DI int my_tid() { int t = tid_raw(); asm volatile("" : "+v"(t)); return t; }
; DI float shfl_xor_l(float v, int mask, int lane) { return __int_as_float(__builtin_amdgcn_ds_bpermute((lane ^ mask) << 2, __float_as_int(v))); }
; DI void ln_phase(const Params& p, const u16* src, const float* g, const float* b, float* dstf, u16* dstb) {
;   const int lane = my_tid() & 63, wid = my_tid() >> 6;
;   const int stride = gridDim.x * 8;
;   int row = blockIdx.x * 8 + wid;
;   u32x2 raw[4], nxt[4];
;   f32x4 gv[4], bv[4];
; #pragma unroll
;   for (int i = 0; i < 4; ++i) { gv[i] = *(const f32x4*)(g + i * 256 + lane * 4); bv[i] = *(const f32x4*)(b + i * 256 + lane * 4); }
;   if (row < S) {
; #pragma unroll
;     for (int i = 0; i < 4; ++i) raw[i] = *(const u32x2*)(src + (size_t)row * D + i * 256 + lane * 4);
;   }
;   for (; row < S; row += stride) {
;     const int rn = row + stride;
;     if (rn < S) {
; #pragma unroll
;       for (int i = 0; i < 4; ++i) nxt[i] = *(const u32x2*)(src + (size_t)rn * D + i * 256 + lane * 4);
;     }
;     f32x4 v[4];
;     float s = 0.f;
; #pragma unroll
;     for (int i = 0; i < 4; ++i) { v[i] = (f32x4){h2lo(raw[i][0]), h2hi(raw[i][0]), h2lo(raw[i][1]), h2hi(raw[i][1])}; s += (v[i][0] + v[i][1]) + (v[i][2] + v[i][3]); }
; #pragma unroll
;     for (int o = 32; o >= 1; o >>= 1) s += shfl_xor_l(s, o, lane);
.LBB0_1322:
	s_or_b64 exec, exec, s[8:9]
	s_waitcnt lgkmcnt(0)
	s_barrier
	s_getreg_b32 s2, hwreg(HW_REG_HW_ID, 0, 6)
	s_lshl_b32 s2, s2, 2
	s_and_b32 s2, s2, 0xfc
	s_add_i32 s2, s2, 0x20040
	v_mov_b32_e32 v0, s2
	ds_read_b32 v0, v0
	s_waitcnt lgkmcnt(0)
	v_readfirstlane_b32 s2, v0
	s_nop 1
	v_lshl_or_b32 v38, s2, 6, v214
	s_getreg_b32 s2, hwreg(HW_REG_HW_ID, 0, 6)
	s_lshl_b32 s2, s2, 2
	s_and_b32 s2, s2, 0xfc
	s_add_i32 s2, s2, 0x20040
	v_mov_b32_e32 v0, s2
	ds_read_b32 v0, v0
	s_waitcnt lgkmcnt(0)
	v_readfirstlane_b32 s2, v0
	s_nop 1
	v_lshl_or_b32 v0, s2, 6, v214
	v_readlane_b32 s2, v255, 12
	v_ashrrev_i32_e32 v39, 6, v0
	s_nop 0
	v_add_u32_e32 v36, s2, v39
	s_movk_i32 s2, 0x4000
	v_cmp_gt_i32_e32 vcc, s2, v36
	s_and_saveexec_b64 s[8:9], vcc
	s_cbranch_execz .LBB0_1343
	s_lshl_b64 s[2:3], s[92:93], 2
	s_add_u32 s22, s84, s2
	s_addc_u32 s23, s85, s3
	v_lshlrev_b32_e32 v42, 2, v38
	s_add_u32 s2, s86, s2
	v_and_b32_e32 v34, 0xfc, v42
	s_addc_u32 s3, s87, s3
	v_lshlrev_b32_e32 v28, 2, v34
	global_load_dwordx4 v[0:3], v28, s[22:23]
	global_load_dwordx4 v[4:7], v28, s[22:23] offset:1024
	global_load_dwordx4 v[8:11], v28, s[2:3]
	global_load_dwordx4 v[12:15], v28, s[2:3] offset:1024
	global_load_dwordx4 v[16:19], v28, s[22:23] offset:2048
	global_load_dwordx4 v[20:23], v28, s[22:23] offset:3072
	global_load_dwordx4 v[24:27], v28, s[2:3] offset:2048
	s_nop 0
	global_load_dwordx4 v[28:31], v28, s[2:3] offset:3072
	v_ashrrev_i32_e32 v37, 31, v36
	v_readlane_b32 s2, v254, 20
	v_lshlrev_b64 v[40:41], 11, v[36:37]
	v_readlane_b32 s3, v254, 21
	v_lshlrev_b32_e32 v64, 1, v34
	s_movk_i32 s7, 0x80
	v_lshl_add_u64 v[32:33], s[2:3], 0, v[40:41]
	v_lshl_add_u64 v[32:33], v[32:33], 0, v[64:65]
	v_lshl_add_u64 v[90:91], v[32:33], 0, v[64:65]
	v_readfirstlane_b32 s100, v39
	v_readlane_b32 s101, v255, 14
	s_lshl_b32 s100, s100, 14
	s_nop 0
	v_mov_b32_e32 v94, s101
	v_readlane_b32 s101, v255, 15
	v_add_u32_e32 v92, s100, v64
	s_nop 1
	v_mov_b32_e32 v95, s101
	s_mov_b32 m0, s100
	s_nop 0
	global_load_lds_dwordx4 v[90:91], off
	global_load_lds_dwordx4 v[90:91], off offset:1024
	v_lshl_add_u64 v[90:91], v[90:91], 0, v[94:95]
	s_add_u32 s100, s100, 0x800
	s_mov_b32 m0, s100
	s_nop 0
	global_load_lds_dwordx4 v[90:91], off
	global_load_lds_dwordx4 v[90:91], off offset:1024
	v_lshl_add_u64 v[90:91], v[90:91], 0, v[94:95]
	s_add_u32 s100, s100, 0x800
	s_mov_b32 m0, s100
	s_nop 0
	global_load_lds_dwordx4 v[90:91], off
	global_load_lds_dwordx4 v[90:91], off offset:1024
	v_lshl_add_u64 v[90:91], v[90:91], 0, v[94:95]
	s_add_u32 s100, s100, 0x800
	s_mov_b32 m0, s100
	s_nop 0
	global_load_lds_dwordx4 v[90:91], off
	global_load_lds_dwordx4 v[90:91], off offset:1024
	v_lshl_add_u64 v[90:91], v[90:91], 0, v[94:95]
	s_add_u32 s100, s100, 0x800
	s_mov_b32 m0, s100
	s_nop 0
	global_load_lds_dwordx4 v[90:91], off
	global_load_lds_dwordx4 v[90:91], off offset:1024
	v_lshl_add_u64 v[90:91], v[90:91], 0, v[94:95]
	s_add_u32 s100, s100, 0x800
	s_mov_b32 m0, s100
	s_nop 0
	global_load_lds_dwordx4 v[90:91], off
	global_load_lds_dwordx4 v[90:91], off offset:1024
	v_lshl_add_u64 v[90:91], v[90:91], 0, v[94:95]
	s_add_u32 s100, s100, 0x800
	s_mov_b32 m0, s100
	s_nop 0
	global_load_lds_dwordx4 v[90:91], off
	global_load_lds_dwordx4 v[90:91], off offset:1024
	v_lshl_add_u64 v[90:91], v[90:91], 0, v[94:95]
	s_add_u32 s100, s100, 0x800
	s_mov_b32 m0, s100
	s_nop 0
	global_load_lds_dwordx4 v[90:91], off
	global_load_lds_dwordx4 v[90:91], off offset:1024
	s_nop 0
	s_and_b64 s[2:3], s[46:47], exec
	v_bfrev_b32_e32 v43, 0.5
	v_readlane_b32 s2, v254, 22
	v_bitop3_b32 v70, v42, s7, v43 bitop3:0x6c
	v_readlane_b32 s7, v255, 13
	v_readlane_b32 s3, v254, 23
	v_readlane_b32 s36, v255, 29
	v_bitop3_b32 v71, v42, 64, v43 bitop3:0x6c
	v_bitop3_b32 v72, v42, 32, v43 bitop3:0x6c
	v_bitop3_b32 v73, v42, 16, v43 bitop3:0x6c
	v_bitop3_b32 v74, v42, 8, v43 bitop3:0x6c
	v_bitop3_b32 v75, v42, 4, v43 bitop3:0x6c
	v_and_b32_e32 v44, 63, v38
	v_add_u32_e32 v38, s7, v39
	v_lshlrev_b64 v[42:43], 12, v[36:37]
	s_cselect_b32 s3, s3, 0
	s_cselect_b32 s2, s2, 0
	v_readlane_b32 s37, v255, 30
	v_ashrrev_i32_e32 v39, 31, v38
	v_lshl_or_b32 v42, v44, 4, v42
	s_cmp_lg_u64 s[36:37], 0
	v_lshlrev_b32_e32 v64, 3, v44
	v_lshlrev_b64 v[38:39], 11, v[38:39]
	v_lshl_add_u64 v[40:41], s[2:3], 0, v[40:41]
	v_lshl_add_u64 v[42:43], s[36:37], 0, v[42:43]
	s_mov_b64 s[2:3], 0x800
	v_mov_b32_e32 v44, 0
	s_mov_b64 s[22:23], 0
	s_cselect_b64 s[28:29], -1, 0
	v_lshl_add_u64 v[38:39], s[90:91], 0, v[38:39]
	v_lshl_add_u64 v[42:43], v[42:43], 0, s[2:3]
	v_mov_b32_e32 v45, v44
	v_mov_b32_e32 v46, v44
	v_mov_b32_e32 v47, v44
	v_mov_b32_e32 v48, v44
	v_mov_b32_e32 v49, v44
	v_mov_b32_e32 v50, v44
	v_mov_b32_e32 v51, v44
	s_branch .LBB0_1325

; DI float h2lo(unsigned u) { return (float)__builtin_bit_cast(f16x2_t, u)[0]; }
; DI float h2hi(unsigned u) { return (float)__builtin_bit_cast(f16x2_t, u)[1]; }
; DI float shfl_xor_l(float v, int mask, int lane) { return __int_as_float(__builtin_amdgcn_ds_bpermute((lane ^ mask) << 2, __float_as_int(v))); }
; DI void ln_phase(const Params& p, const u16* src, const float* g, const float* b, float* dstf, u16* dstb) {
;     ...
;     f32x4 v[4];
;     float s = 0.f;
; #pragma unroll
;     for (int i = 0; i < 4; ++i) { v[i] = (f32x4){h2lo(raw[i][0]), h2hi(raw[i][0]), h2lo(raw[i][1]), h2hi(raw[i][1])}; s += (v[i][0] + v[i][1]) + (v[i][2] + v[i][3]); }
; #pragma unroll
;     for (int o = 32; o >= 1; o >>= 1) s += shfl_xor_l(s, o, lane);
;     const float mu = s * (1.0f / 1024.0f);
;     float q = 0.f;
; #pragma unroll
;     for (int i = 0; i < 4; ++i) { v[i] = v[i] - mu; q += (v[i][0] * v[i][0] + v[i][1] * v[i][1]) + (v[i][2] * v[i][2] + v[i][3] * v[i][3]); }
; #pragma unroll
;     for (int o = 32; o >= 1; o >>= 1) q += shfl_xor_l(q, o, lane);
;     const float rstd = 1.0f / sqrtf(q * (1.0f / 1024.0f) + 1e-5f);
; #pragma unroll
;     for (int i = 0; i < 4; ++i) {
;       const int col = i * 256 + lane * 4;
;       const f32x4 o = v[i] * rstd * gv[i] + bv[i];
;       if (dstf) *(f32x4*)(dstf + (size_t)row * D + col) = o;
.LBB0_1327:
	s_or_b64 exec, exec, s[38:39]
	s_waitcnt vmcnt(14)
	ds_read_b64 v[54:55], v92
	ds_read_b64 v[52:53], v92 offset:512
	ds_read_b64 v[34:35], v92 offset:1024
	ds_read_b64 v[32:33], v92 offset:1536
	v_add_u32_e32 v92, 0x800, v92
	s_waitcnt lgkmcnt(0)
	v_cvt_f32_f16_sdwa v56, v54 dst_sel:DWORD dst_unused:UNUSED_PAD src0_sel:WORD_1
	v_cvt_f32_f16_e32 v58, v54
	v_cvt_f32_f16_sdwa v57, v55 dst_sel:DWORD dst_unused:UNUSED_PAD src0_sel:WORD_1
	v_cvt_f32_f16_e32 v59, v55
	v_cvt_f32_f16_sdwa v60, v52 dst_sel:DWORD dst_unused:UNUSED_PAD src0_sel:WORD_1
	v_cvt_f32_f16_e32 v62, v52
	v_cvt_f32_f16_sdwa v61, v53 dst_sel:DWORD dst_unused:UNUSED_PAD src0_sel:WORD_1
	v_cvt_f32_f16_e32 v63, v53
	v_pk_add_f32 v[56:57], v[58:59], v[56:57]
	v_cvt_f32_f16_sdwa v66, v35 dst_sel:DWORD dst_unused:UNUSED_PAD src0_sel:WORD_1
	v_add_f32_e32 v37, v56, v57
	v_pk_add_f32 v[58:59], v[62:63], v[60:61]
	v_add_f32_e32 v57, 0, v37
	v_pk_add_f32 v[58:59], v[58:59], v[58:59] op_sel_hi:[0,1]
	v_cvt_f32_f16_sdwa v37, v34 dst_sel:DWORD dst_unused:UNUSED_PAD src0_sel:WORD_1
	v_cvt_f32_f16_e32 v61, v34
	v_cvt_f32_f16_e32 v67, v35
	v_cvt_f32_f16_sdwa v60, v32 dst_sel:DWORD dst_unused:UNUSED_PAD src0_sel:WORD_1
	v_cvt_f32_f16_e32 v62, v32
	v_cvt_f32_f16_sdwa v56, v33 dst_sel:DWORD dst_unused:UNUSED_PAD src0_sel:WORD_1
	v_cvt_f32_f16_e32 v58, v33
	v_add_f32_e32 v63, v61, v37
	v_add_f32_e32 v61, v67, v66
	v_pk_add_f32 v[60:61], v[62:63], v[60:61]
	v_pk_add_f32 v[56:57], v[58:59], v[56:57]
	s_nop 0
	v_pk_add_f32 v[56:57], v[60:61], v[56:57]
	s_nop 0
	v_add_f32_e32 v37, v56, v57
	s_nop 1
	v_add_f32_dpp v37, v37, v37 quad_perm:[1,0,3,2] row_mask:0xf bank_mask:0xf
	s_nop 1
	v_add_f32_dpp v37, v37, v37 quad_perm:[2,3,0,1] row_mask:0xf bank_mask:0xf
	s_nop 1
	v_add_f32_dpp v37, v37, v37 row_half_mirror row_mask:0xf bank_mask:0xf
	s_nop 1
	v_add_f32_dpp v37, v37, v37 row_mirror row_mask:0xf bank_mask:0xf
	v_mov_b32_e32 v56, v37
	s_nop 1
	v_permlane16_swap_b32 v56, v37
	v_add_f32_e32 v37, v37, v56
	v_mov_b32_e32 v56, v37
	s_nop 1
	v_permlane32_swap_b32 v56, v37
	v_add_f32_e32 v37, v37, v56
	v_fma_mix_f32 v67, v37, s65, v54 op_sel:[0,0,1] op_sel_hi:[0,0,1]
	v_fma_mix_f32 v66, v37, s65, v54 op_sel_hi:[0,0,1]
	v_fma_mix_f32 v77, v37, s65, v55 op_sel:[0,0,1] op_sel_hi:[0,0,1]
	v_fma_mix_f32 v76, v37, s65, v55 op_sel_hi:[0,0,1]
	v_fma_mix_f32 v61, v37, s65, v53 op_sel:[0,0,1] op_sel_hi:[0,0,1]
	v_fma_mix_f32 v60, v37, s65, v53 op_sel_hi:[0,0,1]
	v_fma_mix_f32 v63, v37, s65, v52 op_sel:[0,0,1] op_sel_hi:[0,0,1]
	v_fma_mix_f32 v62, v37, s65, v52 op_sel_hi:[0,0,1]
	v_pk_mul_f32 v[52:53], v[76:77], v[76:77]
	v_pk_mul_f32 v[54:55], v[66:67], v[66:67]
	v_pk_mul_f32 v[56:57], v[60:61], v[60:61]
	v_pk_mov_b32 v[58:59], v[54:55], v[52:53] op_sel:[1,0]
	v_mov_b32_e32 v55, v53
	v_pk_add_f32 v[52:53], v[58:59], v[54:55]
	v_fma_mix_f32 v58, v37, s65, v34 op_sel_hi:[0,0,1]
	v_pk_add_f32 v[68:69], v[52:53], v[52:53] op_sel_hi:[0,1]
	v_pk_mul_f32 v[52:53], v[62:63], v[62:63]
	v_fma_mix_f32 v59, v37, s65, v34 op_sel:[0,0,1] op_sel_hi:[0,0,1]
	v_mul_f32_e32 v34, v58, v58
	v_pk_mov_b32 v[54:55], v[52:53], v[56:57] op_sel:[1,0]
	v_mov_b32_e32 v53, v57
	v_fma_mix_f32 v57, v37, s65, v35 op_sel:[0,0,1] op_sel_hi:[0,0,1]
	v_fma_mix_f32 v56, v37, s65, v35 op_sel_hi:[0,0,1]
	v_pk_fma_f32 v[34:35], v[58:59], v[58:59], v[34:35] op_sel_hi:[1,1,0]
	v_pk_add_f32 v[52:53], v[54:55], v[52:53]
	v_mul_f32_e32 v34, v56, v56
	v_pk_add_f32 v[78:79], v[52:53], v[52:53] op_sel_hi:[0,1]
	v_pk_fma_f32 v[80:81], v[56:57], v[56:57], v[34:35] op_sel_hi:[1,1,0]
	v_fma_mix_f32 v53, v37, s65, v33 op_sel:[0,0,1] op_sel_hi:[0,0,1]
	v_fma_mix_f32 v52, v37, s65, v33 op_sel_hi:[0,0,1]
	v_fma_mix_f32 v55, v37, s65, v32 op_sel:[0,0,1] op_sel_hi:[0,0,1]
	v_fma_mix_f32 v54, v37, s65, v32 op_sel_hi:[0,0,1]
	v_mul_f32_e32 v34, v54, v54
	v_mul_f32_e32 v80, v55, v55
	v_mul_f32_e32 v68, v52, v52
	v_mul_f32_e32 v78, v53, v53
	v_pk_add_f32 v[32:33], v[34:35], v[80:81]
	v_pk_add_f32 v[34:35], v[68:69], v[78:79]
	s_nop 0
	v_pk_add_f32 v[32:33], v[32:33], v[34:35]
	s_nop 0
	v_add_f32_e32 v32, v32, v33
	s_nop 1
	v_add_f32_dpp v32, v32, v32 quad_perm:[1,0,3,2] row_mask:0xf bank_mask:0xf
	s_nop 1
	v_add_f32_dpp v32, v32, v32 quad_perm:[2,3,0,1] row_mask:0xf bank_mask:0xf
	s_nop 1
	v_add_f32_dpp v32, v32, v32 row_half_mirror row_mask:0xf bank_mask:0xf
	s_nop 1
	v_add_f32_dpp v32, v32, v32 row_mirror row_mask:0xf bank_mask:0xf
	v_mov_b32_e32 v33, v32
	s_nop 1
	v_permlane16_swap_b32 v33, v32
	v_add_f32_e32 v32, v32, v33
	v_mov_b32_e32 v33, v32
	s_nop 1
	v_permlane32_swap_b32 v33, v32
	v_add_f32_e32 v32, v32, v33
	v_mov_b32_e32 v33, 0x3727c5ac
	v_fmamk_f32 v32, v32, 0x3a800000, v33
	v_mul_f32_e32 v33, 0x4f800000, v32
	v_cmp_gt_f32_e32 vcc, s66, v32
	s_nop 1
	v_cndmask_b32_e32 v32, v32, v33, vcc
	v_sqrt_f32_e32 v33, v32
	s_nop 0
	v_add_u32_e32 v34, -1, v33
	v_add_u32_e32 v35, 1, v33
	v_fma_f32 v37, -v34, v33, v32
	v_fma_f32 v68, -v35, v33, v32
	v_cmp_ge_f32_e64 s[38:39], 0, v37
	s_nop 1
	v_cndmask_b32_e64 v33, v33, v34, s[38:39]
	v_cmp_lt_f32_e64 s[38:39], 0, v68
	s_nop 1
	v_cndmask_b32_e64 v33, v33, v35, s[38:39]
	v_mul_f32_e32 v34, 0x37800000, v33
	v_cndmask_b32_e32 v33, v33, v34, vcc
	v_mov_b32_e32 v34, 0x260
	v_cmp_class_f32_e32 vcc, v32, v34
	s_nop 1
	v_cndmask_b32_e32 v32, v33, v32, vcc
	v_div_scale_f32 v33, s[2:3], v32, v32, 1.0
	v_rcp_f32_e32 v34, v33
	v_div_scale_f32 v35, vcc, 1.0, v32, 1.0
	v_fma_f32 v37, -v33, v34, 1.0
	v_fmac_f32_e32 v34, v37, v34
	v_mul_f32_e32 v37, v35, v34
	v_fma_f32 v68, -v33, v37, v35
	v_fmac_f32_e32 v37, v68, v34
	v_fma_f32 v33, -v33, v37, v35
	v_div_fmas_f32 v33, v33, v34, v37
	v_div_fixup_f32 v68, v33, v32, 1.0
	v_pk_mul_f32 v[32:33], v[66:67], v[68:69] op_sel_hi:[1,0]
	v_pk_mul_f32 v[34:35], v[76:77], v[68:69] op_sel_hi:[1,0]
	v_cndmask_b32_e64 v37, 0, 1, s[28:29]
	v_pk_fma_f32 v[34:35], v[2:3], v[34:35], v[10:11]
	v_cmp_ne_u32_e64 s[38:39], 1, v37
	s_andn2_b64 vcc, exec, s[28:29]
	v_pk_fma_f32 v[32:33], v[0:1], v[32:33], v[8:9]
	s_cbranch_vccnz .LBB0_1329
	global_store_dwordx4 v[42:43], v[32:35], off offset:-2048
